# GEMM unit prologues: removed the redundant second zero-fill of the 128 accumulators (already zero from the fill before the K-loop skip test) in all six GEMMs
# baseline (speedup 1.0000x reference)
.LBB0_124:
	v_mov_b32_e32 v125, 0
	s_andn2_b64 vcc, exec, s[14:15]
	v_mov_b32_e32 v124, v125
	v_mov_b32_e32 v123, v125
	v_mov_b32_e32 v122, v125
	v_mov_b32_e32 v129, v125
	v_mov_b32_e32 v128, v125
	v_mov_b32_e32 v127, v125
	v_mov_b32_e32 v126, v125
	v_mov_b32_e32 v113, v125
	v_mov_b32_e32 v112, v125
	v_mov_b32_e32 v111, v125
	v_mov_b32_e32 v110, v125
	v_mov_b32_e32 v109, v125
	v_mov_b32_e32 v108, v125
	v_mov_b32_e32 v107, v125
	v_mov_b32_e32 v106, v125
	s_waitcnt vmcnt(0)
	v_mov_b32_e32 v97, v125
	v_mov_b32_e32 v96, v125
	v_mov_b32_e32 v95, v125
	v_mov_b32_e32 v94, v125
	v_mov_b32_e32 v93, v125
	v_mov_b32_e32 v92, v125
	v_mov_b32_e32 v91, v125
	v_mov_b32_e32 v90, v125
	v_mov_b32_e32 v81, v125
	v_mov_b32_e32 v80, v125
	v_mov_b32_e32 v79, v125
	v_mov_b32_e32 v78, v125
	v_mov_b32_e32 v77, v125
	v_mov_b32_e32 v76, v125
	v_mov_b32_e32 v75, v125
	v_mov_b32_e32 v74, v125
	v_mov_b32_e32 v121, v125
	v_mov_b32_e32 v120, v125
	v_mov_b32_e32 v119, v125
	v_mov_b32_e32 v118, v125
	v_mov_b32_e32 v117, v125
	v_mov_b32_e32 v116, v125
	v_mov_b32_e32 v115, v125
	v_mov_b32_e32 v114, v125
	v_mov_b32_e32 v105, v125
	v_mov_b32_e32 v104, v125
	v_mov_b32_e32 v103, v125
	v_mov_b32_e32 v102, v125
	v_mov_b32_e32 v101, v125
	v_mov_b32_e32 v100, v125
	v_mov_b32_e32 v99, v125
	v_mov_b32_e32 v98, v125
	v_mov_b32_e32 v89, v125
	v_mov_b32_e32 v88, v125
	v_mov_b32_e32 v87, v125
	v_mov_b32_e32 v86, v125
	v_mov_b32_e32 v85, v125
	v_mov_b32_e32 v84, v125
	v_mov_b32_e32 v83, v125
	v_mov_b32_e32 v82, v125
	v_mov_b32_e32 v73, v125
	v_mov_b32_e32 v72, v125
	v_mov_b32_e32 v71, v125
	v_mov_b32_e32 v70, v125
	v_mov_b32_e32 v69, v125
	v_mov_b32_e32 v68, v125
	v_mov_b32_e32 v67, v125
	v_mov_b32_e32 v66, v125
	v_mov_b32_e32 v65, v125
	v_mov_b32_e32 v64, v125
	v_mov_b32_e32 v63, v125
	v_mov_b32_e32 v62, v125
	v_mov_b32_e32 v61, v125
	v_mov_b32_e32 v60, v125
	v_mov_b32_e32 v59, v125
	v_mov_b32_e32 v58, v125
	v_mov_b32_e32 v49, v125
	v_mov_b32_e32 v48, v125
	v_mov_b32_e32 v47, v125
	v_mov_b32_e32 v46, v125
	v_mov_b32_e32 v45, v125
	v_mov_b32_e32 v44, v125
	v_mov_b32_e32 v43, v125
	v_mov_b32_e32 v42, v125
	v_mov_b32_e32 v33, v125
	v_mov_b32_e32 v32, v125
	v_mov_b32_e32 v31, v125
	v_mov_b32_e32 v30, v125
	v_mov_b32_e32 v29, v125
	v_mov_b32_e32 v28, v125
	v_mov_b32_e32 v27, v125
	v_mov_b32_e32 v26, v125
	v_mov_b32_e32 v17, v125
	v_mov_b32_e32 v16, v125
	v_mov_b32_e32 v15, v125
	v_mov_b32_e32 v14, v125
	v_mov_b32_e32 v13, v125
	v_mov_b32_e32 v12, v125
	v_mov_b32_e32 v11, v125
	v_mov_b32_e32 v10, v125
	v_mov_b32_e32 v57, v125
	v_mov_b32_e32 v56, v125
	v_mov_b32_e32 v55, v125
	v_mov_b32_e32 v54, v125
	v_mov_b32_e32 v53, v125
	v_mov_b32_e32 v52, v125
	v_mov_b32_e32 v51, v125
	v_mov_b32_e32 v50, v125
	v_mov_b32_e32 v41, v125
	v_mov_b32_e32 v40, v125
	v_mov_b32_e32 v39, v125
	v_mov_b32_e32 v38, v125
	v_mov_b32_e32 v37, v125
	v_mov_b32_e32 v36, v125
	v_mov_b32_e32 v35, v125
	v_mov_b32_e32 v34, v125
	v_mov_b32_e32 v25, v125
	v_mov_b32_e32 v24, v125
	v_mov_b32_e32 v23, v125
	v_mov_b32_e32 v22, v125
	v_mov_b32_e32 v21, v125
	v_mov_b32_e32 v20, v125
	v_mov_b32_e32 v19, v125
	v_mov_b32_e32 v18, v125
	v_mov_b32_e32 v9, v125
	v_mov_b32_e32 v8, v125
	v_mov_b32_e32 v7, v125
	v_mov_b32_e32 v6, v125
	v_mov_b32_e32 v5, v125
	v_mov_b32_e32 v4, v125
	v_mov_b32_e32 v3, v125
	v_mov_b32_e32 v2, v125
	s_cbranch_vccnz .LBB0_127
	s_add_u32 s20, s20, 0x80
	s_addc_u32 s21, s21, 0
	s_add_u32 s43, s22, 0x100
	s_addc_u32 s44, s23, 0
	s_mov_b32 s22, 0
	s_mov_b64 s[50:51], 0x80

.LBB0_426:
	v_mov_b32_e32 v129, 0
	s_andn2_b64 vcc, exec, s[18:19]
	v_mov_b32_e32 v128, v129
	v_mov_b32_e32 v127, v129
	v_mov_b32_e32 v126, v129
	v_mov_b32_e32 v125, v129
	v_mov_b32_e32 v124, v129
	v_mov_b32_e32 v123, v129
	v_mov_b32_e32 v122, v129
	v_mov_b32_e32 v113, v129
	v_mov_b32_e32 v112, v129
	v_mov_b32_e32 v111, v129
	v_mov_b32_e32 v110, v129
	v_mov_b32_e32 v109, v129
	v_mov_b32_e32 v108, v129
	v_mov_b32_e32 v107, v129
	v_mov_b32_e32 v106, v129
	v_mov_b32_e32 v97, v129
	v_mov_b32_e32 v96, v129
	v_mov_b32_e32 v95, v129
	v_mov_b32_e32 v94, v129
	v_mov_b32_e32 v93, v129
	v_mov_b32_e32 v92, v129
	v_mov_b32_e32 v91, v129
	v_mov_b32_e32 v90, v129
	v_mov_b32_e32 v81, v129
	v_mov_b32_e32 v80, v129
	v_mov_b32_e32 v79, v129
	v_mov_b32_e32 v78, v129
	v_mov_b32_e32 v77, v129
	v_mov_b32_e32 v76, v129
	v_mov_b32_e32 v75, v129
	v_mov_b32_e32 v74, v129
	v_mov_b32_e32 v121, v129
	v_mov_b32_e32 v120, v129
	v_mov_b32_e32 v119, v129
	v_mov_b32_e32 v118, v129
	v_mov_b32_e32 v117, v129
	v_mov_b32_e32 v116, v129
	v_mov_b32_e32 v115, v129
	v_mov_b32_e32 v114, v129
	v_mov_b32_e32 v105, v129
	v_mov_b32_e32 v104, v129
	v_mov_b32_e32 v103, v129
	v_mov_b32_e32 v102, v129
	v_mov_b32_e32 v101, v129
	v_mov_b32_e32 v100, v129
	v_mov_b32_e32 v99, v129
	v_mov_b32_e32 v98, v129
	v_mov_b32_e32 v89, v129
	v_mov_b32_e32 v88, v129
	v_mov_b32_e32 v87, v129
	v_mov_b32_e32 v86, v129
	v_mov_b32_e32 v85, v129
	v_mov_b32_e32 v84, v129
	v_mov_b32_e32 v83, v129
	v_mov_b32_e32 v82, v129
	v_mov_b32_e32 v73, v129
	v_mov_b32_e32 v72, v129
	v_mov_b32_e32 v71, v129
	v_mov_b32_e32 v70, v129
	v_mov_b32_e32 v69, v129
	v_mov_b32_e32 v68, v129
	v_mov_b32_e32 v67, v129
	v_mov_b32_e32 v66, v129
	v_mov_b32_e32 v65, v129
	v_mov_b32_e32 v64, v129
	v_mov_b32_e32 v63, v129
	v_mov_b32_e32 v62, v129
	v_mov_b32_e32 v61, v129
	v_mov_b32_e32 v60, v129
	v_mov_b32_e32 v59, v129
	v_mov_b32_e32 v58, v129
	v_mov_b32_e32 v49, v129
	v_mov_b32_e32 v48, v129
	v_mov_b32_e32 v47, v129
	v_mov_b32_e32 v46, v129
	v_mov_b32_e32 v45, v129
	v_mov_b32_e32 v44, v129
	v_mov_b32_e32 v43, v129
	v_mov_b32_e32 v42, v129
	v_mov_b32_e32 v33, v129
	v_mov_b32_e32 v32, v129
	v_mov_b32_e32 v31, v129
	v_mov_b32_e32 v30, v129
	v_mov_b32_e32 v29, v129
	v_mov_b32_e32 v28, v129
	v_mov_b32_e32 v27, v129
	v_mov_b32_e32 v26, v129
	v_mov_b32_e32 v17, v129
	v_mov_b32_e32 v16, v129
	v_mov_b32_e32 v15, v129
	v_mov_b32_e32 v14, v129
	v_mov_b32_e32 v13, v129
	v_mov_b32_e32 v12, v129
	v_mov_b32_e32 v11, v129
	v_mov_b32_e32 v10, v129
	v_mov_b32_e32 v57, v129
	v_mov_b32_e32 v56, v129
	v_mov_b32_e32 v55, v129
	v_mov_b32_e32 v54, v129
	v_mov_b32_e32 v53, v129
	v_mov_b32_e32 v52, v129
	v_mov_b32_e32 v51, v129
	v_mov_b32_e32 v50, v129
	v_mov_b32_e32 v41, v129
	v_mov_b32_e32 v40, v129
	v_mov_b32_e32 v39, v129
	v_mov_b32_e32 v38, v129
	v_mov_b32_e32 v37, v129
	v_mov_b32_e32 v36, v129
	v_mov_b32_e32 v35, v129
	v_mov_b32_e32 v34, v129
	v_mov_b32_e32 v25, v129
	v_mov_b32_e32 v24, v129
	v_mov_b32_e32 v23, v129
	v_mov_b32_e32 v22, v129
	v_mov_b32_e32 v21, v129
	v_mov_b32_e32 v20, v129
	v_mov_b32_e32 v19, v129
	v_mov_b32_e32 v18, v129
	v_mov_b32_e32 v9, v129
	v_mov_b32_e32 v8, v129
	v_mov_b32_e32 v7, v129
	v_mov_b32_e32 v6, v129
	v_mov_b32_e32 v5, v129
	v_mov_b32_e32 v4, v129
	v_mov_b32_e32 v3, v129
	v_mov_b32_e32 v2, v129
	s_cbranch_vccnz .LBB0_430
	s_add_u32 s0, s28, 0x80
	s_addc_u32 s1, s29, 0
	s_add_u32 s28, s26, 0x100
	s_addc_u32 s29, s27, 0
	s_mov_b32 s26, 0
	s_mov_b64 s[64:65], 0x80

.LBB0_452:
	v_mov_b32_e32 v125, 0
	s_andn2_b64 vcc, exec, s[12:13]
	v_mov_b32_e32 v124, v125
	v_mov_b32_e32 v123, v125
	v_mov_b32_e32 v122, v125
	v_mov_b32_e32 v129, v125
	v_mov_b32_e32 v128, v125
	v_mov_b32_e32 v127, v125
	v_mov_b32_e32 v126, v125
	v_mov_b32_e32 v113, v125
	v_mov_b32_e32 v112, v125
	v_mov_b32_e32 v111, v125
	v_mov_b32_e32 v110, v125
	v_mov_b32_e32 v109, v125
	v_mov_b32_e32 v108, v125
	v_mov_b32_e32 v107, v125
	v_mov_b32_e32 v106, v125
	v_mov_b32_e32 v97, v125
	v_mov_b32_e32 v96, v125
	v_mov_b32_e32 v95, v125
	v_mov_b32_e32 v94, v125
	v_mov_b32_e32 v93, v125
	v_mov_b32_e32 v92, v125
	v_mov_b32_e32 v91, v125
	v_mov_b32_e32 v90, v125
	v_mov_b32_e32 v81, v125
	v_mov_b32_e32 v80, v125
	v_mov_b32_e32 v79, v125
	v_mov_b32_e32 v78, v125
	v_mov_b32_e32 v77, v125
	v_mov_b32_e32 v76, v125
	v_mov_b32_e32 v75, v125
	v_mov_b32_e32 v74, v125
	v_mov_b32_e32 v121, v125
	v_mov_b32_e32 v120, v125
	v_mov_b32_e32 v119, v125
	v_mov_b32_e32 v118, v125
	v_mov_b32_e32 v117, v125
	v_mov_b32_e32 v116, v125
	v_mov_b32_e32 v115, v125
	v_mov_b32_e32 v114, v125
	v_mov_b32_e32 v105, v125
	v_mov_b32_e32 v104, v125
	v_mov_b32_e32 v103, v125
	v_mov_b32_e32 v102, v125
	v_mov_b32_e32 v101, v125
	v_mov_b32_e32 v100, v125
	v_mov_b32_e32 v99, v125
	v_mov_b32_e32 v98, v125
	v_mov_b32_e32 v89, v125
	v_mov_b32_e32 v88, v125
	v_mov_b32_e32 v87, v125
	v_mov_b32_e32 v86, v125
	v_mov_b32_e32 v85, v125
	v_mov_b32_e32 v84, v125
	v_mov_b32_e32 v83, v125
	v_mov_b32_e32 v82, v125
	v_mov_b32_e32 v73, v125
	v_mov_b32_e32 v72, v125
	v_mov_b32_e32 v71, v125
	v_mov_b32_e32 v70, v125
	v_mov_b32_e32 v69, v125
	v_mov_b32_e32 v68, v125
	v_mov_b32_e32 v67, v125
	v_mov_b32_e32 v66, v125
	v_mov_b32_e32 v65, v125
	v_mov_b32_e32 v64, v125
	v_mov_b32_e32 v63, v125
	v_mov_b32_e32 v62, v125
	v_mov_b32_e32 v61, v125
	v_mov_b32_e32 v60, v125
	v_mov_b32_e32 v59, v125
	v_mov_b32_e32 v58, v125
	v_mov_b32_e32 v49, v125
	v_mov_b32_e32 v48, v125
	v_mov_b32_e32 v47, v125
	v_mov_b32_e32 v46, v125
	v_mov_b32_e32 v45, v125
	v_mov_b32_e32 v44, v125
	v_mov_b32_e32 v43, v125
	v_mov_b32_e32 v42, v125
	v_mov_b32_e32 v33, v125
	v_mov_b32_e32 v32, v125
	v_mov_b32_e32 v31, v125
	v_mov_b32_e32 v30, v125
	v_mov_b32_e32 v29, v125
	v_mov_b32_e32 v28, v125
	v_mov_b32_e32 v27, v125
	v_mov_b32_e32 v26, v125
	v_mov_b32_e32 v17, v125
	v_mov_b32_e32 v16, v125
	v_mov_b32_e32 v15, v125
	v_mov_b32_e32 v14, v125
	v_mov_b32_e32 v13, v125
	v_mov_b32_e32 v12, v125
	v_mov_b32_e32 v11, v125
	v_mov_b32_e32 v10, v125
	v_mov_b32_e32 v57, v125
	v_mov_b32_e32 v56, v125
	v_mov_b32_e32 v55, v125
	v_mov_b32_e32 v54, v125
	v_mov_b32_e32 v53, v125
	v_mov_b32_e32 v52, v125
	v_mov_b32_e32 v51, v125
	v_mov_b32_e32 v50, v125
	v_mov_b32_e32 v41, v125
	v_mov_b32_e32 v40, v125
	v_mov_b32_e32 v39, v125
	v_mov_b32_e32 v38, v125
	v_mov_b32_e32 v37, v125
	v_mov_b32_e32 v36, v125
	v_mov_b32_e32 v35, v125
	v_mov_b32_e32 v34, v125
	v_mov_b32_e32 v25, v125
	v_mov_b32_e32 v24, v125
	v_mov_b32_e32 v23, v125
	v_mov_b32_e32 v22, v125
	v_mov_b32_e32 v21, v125
	v_mov_b32_e32 v20, v125
	v_mov_b32_e32 v19, v125
	v_mov_b32_e32 v18, v125
	v_mov_b32_e32 v9, v125
	v_mov_b32_e32 v8, v125
	v_mov_b32_e32 v7, v125
	v_mov_b32_e32 v6, v125
	v_mov_b32_e32 v5, v125
	v_mov_b32_e32 v4, v125
	v_mov_b32_e32 v3, v125
	v_mov_b32_e32 v2, v125
	s_cbranch_vccnz .LBB0_455
	s_add_u32 s18, s18, 0x80
	s_addc_u32 s19, s19, 0
	s_add_u32 s43, s20, 0x100
	s_addc_u32 s44, s21, 0
	s_mov_b32 s20, 0
	s_mov_b64 s[50:51], 0x80

.LBB0_609:
	v_mov_b32_e32 v129, 0
	s_andn2_b64 vcc, exec, s[14:15]
	v_mov_b32_e32 v128, v129
	v_mov_b32_e32 v127, v129
	v_mov_b32_e32 v126, v129
	v_mov_b32_e32 v125, v129
	v_mov_b32_e32 v124, v129
	v_mov_b32_e32 v123, v129
	v_mov_b32_e32 v122, v129
	v_mov_b32_e32 v113, v129
	v_mov_b32_e32 v112, v129
	v_mov_b32_e32 v111, v129
	v_mov_b32_e32 v110, v129
	v_mov_b32_e32 v109, v129
	v_mov_b32_e32 v108, v129
	v_mov_b32_e32 v107, v129
	v_mov_b32_e32 v106, v129
	s_waitcnt vmcnt(0)
	v_mov_b32_e32 v97, v129
	v_mov_b32_e32 v96, v129
	v_mov_b32_e32 v95, v129
	v_mov_b32_e32 v94, v129
	v_mov_b32_e32 v93, v129
	v_mov_b32_e32 v92, v129
	v_mov_b32_e32 v91, v129
	v_mov_b32_e32 v90, v129
	v_mov_b32_e32 v81, v129
	v_mov_b32_e32 v80, v129
	v_mov_b32_e32 v79, v129
	v_mov_b32_e32 v78, v129
	v_mov_b32_e32 v77, v129
	v_mov_b32_e32 v76, v129
	v_mov_b32_e32 v75, v129
	v_mov_b32_e32 v74, v129
	v_mov_b32_e32 v121, v129
	v_mov_b32_e32 v120, v129
	v_mov_b32_e32 v119, v129
	v_mov_b32_e32 v118, v129
	v_mov_b32_e32 v117, v129
	v_mov_b32_e32 v116, v129
	v_mov_b32_e32 v115, v129
	v_mov_b32_e32 v114, v129
	v_mov_b32_e32 v105, v129
	v_mov_b32_e32 v104, v129
	v_mov_b32_e32 v103, v129
	v_mov_b32_e32 v102, v129
	v_mov_b32_e32 v101, v129
	v_mov_b32_e32 v100, v129
	v_mov_b32_e32 v99, v129
	v_mov_b32_e32 v98, v129
	v_mov_b32_e32 v89, v129
	v_mov_b32_e32 v88, v129
	v_mov_b32_e32 v87, v129
	v_mov_b32_e32 v86, v129
	v_mov_b32_e32 v85, v129
	v_mov_b32_e32 v84, v129
	v_mov_b32_e32 v83, v129
	v_mov_b32_e32 v82, v129
	v_mov_b32_e32 v73, v129
	v_mov_b32_e32 v72, v129
	v_mov_b32_e32 v71, v129
	v_mov_b32_e32 v70, v129
	v_mov_b32_e32 v69, v129
	v_mov_b32_e32 v68, v129
	v_mov_b32_e32 v67, v129
	v_mov_b32_e32 v66, v129
	v_mov_b32_e32 v65, v129
	v_mov_b32_e32 v64, v129
	v_mov_b32_e32 v63, v129
	v_mov_b32_e32 v62, v129
	v_mov_b32_e32 v61, v129
	v_mov_b32_e32 v60, v129
	v_mov_b32_e32 v59, v129
	v_mov_b32_e32 v58, v129
	v_mov_b32_e32 v49, v129
	v_mov_b32_e32 v48, v129
	v_mov_b32_e32 v47, v129
	v_mov_b32_e32 v46, v129
	v_mov_b32_e32 v45, v129
	v_mov_b32_e32 v44, v129
	v_mov_b32_e32 v43, v129
	v_mov_b32_e32 v42, v129
	v_mov_b32_e32 v33, v129
	v_mov_b32_e32 v32, v129
	v_mov_b32_e32 v31, v129
	v_mov_b32_e32 v30, v129
	v_mov_b32_e32 v29, v129
	v_mov_b32_e32 v28, v129
	v_mov_b32_e32 v27, v129
	v_mov_b32_e32 v26, v129
	v_mov_b32_e32 v17, v129
	v_mov_b32_e32 v16, v129
	v_mov_b32_e32 v15, v129
	v_mov_b32_e32 v14, v129
	v_mov_b32_e32 v13, v129
	v_mov_b32_e32 v12, v129
	v_mov_b32_e32 v11, v129
	v_mov_b32_e32 v10, v129
	v_mov_b32_e32 v57, v129
	v_mov_b32_e32 v56, v129
	v_mov_b32_e32 v55, v129
	v_mov_b32_e32 v54, v129
	v_mov_b32_e32 v53, v129
	v_mov_b32_e32 v52, v129
	v_mov_b32_e32 v51, v129
	v_mov_b32_e32 v50, v129
	v_mov_b32_e32 v41, v129
	v_mov_b32_e32 v40, v129
	v_mov_b32_e32 v39, v129
	v_mov_b32_e32 v38, v129
	v_mov_b32_e32 v37, v129
	v_mov_b32_e32 v36, v129
	v_mov_b32_e32 v35, v129
	v_mov_b32_e32 v34, v129
	v_mov_b32_e32 v25, v129
	v_mov_b32_e32 v24, v129
	v_mov_b32_e32 v23, v129
	v_mov_b32_e32 v22, v129
	v_mov_b32_e32 v21, v129
	v_mov_b32_e32 v20, v129
	v_mov_b32_e32 v19, v129
	v_mov_b32_e32 v18, v129
	v_mov_b32_e32 v9, v129
	v_mov_b32_e32 v8, v129
	v_mov_b32_e32 v7, v129
	v_mov_b32_e32 v6, v129
	v_mov_b32_e32 v5, v129
	v_mov_b32_e32 v4, v129
	v_mov_b32_e32 v3, v129
	v_mov_b32_e32 v2, v129
	s_cbranch_vccnz .LBB0_612
	s_add_u32 s20, s20, 0x80
	s_addc_u32 s21, s21, 0
	s_add_u32 s45, s22, 0x100
	s_addc_u32 s46, s23, 0
	s_mov_b32 s22, 0
	s_mov_b64 s[52:53], 0x80

.LBB0_737:
	v_mov_b32_e32 v125, 0
	s_andn2_b64 vcc, exec, s[20:21]
	v_mov_b32_e32 v124, v125
	v_mov_b32_e32 v123, v125
	v_mov_b32_e32 v122, v125
	v_mov_b32_e32 v121, v125
	v_mov_b32_e32 v120, v125
	v_mov_b32_e32 v119, v125
	v_mov_b32_e32 v118, v125
	v_mov_b32_e32 v57, v125
	v_mov_b32_e32 v56, v125
	v_mov_b32_e32 v55, v125
	v_mov_b32_e32 v54, v125
	v_mov_b32_e32 v113, v125
	v_mov_b32_e32 v112, v125
	v_mov_b32_e32 v111, v125
	v_mov_b32_e32 v110, v125
	v_mov_b32_e32 v49, v125
	v_mov_b32_e32 v48, v125
	v_mov_b32_e32 v47, v125
	v_mov_b32_e32 v46, v125
	v_mov_b32_e32 v105, v125
	v_mov_b32_e32 v104, v125
	v_mov_b32_e32 v103, v125
	v_mov_b32_e32 v102, v125
	v_mov_b32_e32 v129, v125
	v_mov_b32_e32 v128, v125
	v_mov_b32_e32 v127, v125
	v_mov_b32_e32 v126, v125
	v_mov_b32_e32 v117, v125
	v_mov_b32_e32 v116, v125
	v_mov_b32_e32 v115, v125
	v_mov_b32_e32 v114, v125
	v_mov_b32_e32 v53, v125
	v_mov_b32_e32 v52, v125
	v_mov_b32_e32 v51, v125
	v_mov_b32_e32 v50, v125
	v_mov_b32_e32 v109, v125
	v_mov_b32_e32 v108, v125
	v_mov_b32_e32 v107, v125
	v_mov_b32_e32 v106, v125
	v_mov_b32_e32 v45, v125
	v_mov_b32_e32 v44, v125
	v_mov_b32_e32 v43, v125
	v_mov_b32_e32 v42, v125
	s_waitcnt vmcnt(0)
	v_mov_b32_e32 v101, v125
	v_mov_b32_e32 v100, v125
	v_mov_b32_e32 v99, v125
	v_mov_b32_e32 v98, v125
	v_mov_b32_e32 v97, v125
	v_mov_b32_e32 v96, v125
	v_mov_b32_e32 v95, v125
	v_mov_b32_e32 v94, v125
	v_mov_b32_e32 v89, v125
	v_mov_b32_e32 v88, v125
	v_mov_b32_e32 v87, v125
	v_mov_b32_e32 v86, v125
	v_mov_b32_e32 v25, v125
	v_mov_b32_e32 v24, v125
	v_mov_b32_e32 v23, v125
	v_mov_b32_e32 v22, v125
	v_mov_b32_e32 v81, v125
	v_mov_b32_e32 v80, v125
	v_mov_b32_e32 v79, v125
	v_mov_b32_e32 v78, v125
	v_mov_b32_e32 v17, v125
	v_mov_b32_e32 v16, v125
	v_mov_b32_e32 v15, v125
	v_mov_b32_e32 v14, v125
	v_mov_b32_e32 v73, v125
	v_mov_b32_e32 v72, v125
	v_mov_b32_e32 v71, v125
	v_mov_b32_e32 v70, v125
	v_mov_b32_e32 v93, v125
	v_mov_b32_e32 v92, v125
	v_mov_b32_e32 v91, v125
	v_mov_b32_e32 v90, v125
	v_mov_b32_e32 v85, v125
	v_mov_b32_e32 v84, v125
	v_mov_b32_e32 v83, v125
	v_mov_b32_e32 v82, v125
	v_mov_b32_e32 v21, v125
	v_mov_b32_e32 v20, v125
	v_mov_b32_e32 v19, v125
	v_mov_b32_e32 v18, v125
	v_mov_b32_e32 v77, v125
	v_mov_b32_e32 v76, v125
	v_mov_b32_e32 v75, v125
	v_mov_b32_e32 v74, v125
	v_mov_b32_e32 v13, v125
	v_mov_b32_e32 v12, v125
	v_mov_b32_e32 v11, v125
	v_mov_b32_e32 v10, v125
	v_mov_b32_e32 v69, v125
	v_mov_b32_e32 v68, v125
	v_mov_b32_e32 v67, v125
	v_mov_b32_e32 v66, v125
	v_mov_b32_e32 v5, v125
	v_mov_b32_e32 v4, v125
	v_mov_b32_e32 v3, v125
	v_mov_b32_e32 v2, v125
	v_mov_b32_e32 v29, v125
	v_mov_b32_e32 v28, v125
	v_mov_b32_e32 v27, v125
	v_mov_b32_e32 v26, v125
	v_mov_b32_e32 v9, v125
	v_mov_b32_e32 v8, v125
	v_mov_b32_e32 v7, v125
	v_mov_b32_e32 v6, v125
	v_mov_b32_e32 v33, v125
	v_mov_b32_e32 v32, v125
	v_mov_b32_e32 v31, v125
	v_mov_b32_e32 v30, v125
	v_mov_b32_e32 v37, v125
	v_mov_b32_e32 v36, v125
	v_mov_b32_e32 v35, v125
	v_mov_b32_e32 v34, v125
	v_mov_b32_e32 v65, v125
	v_mov_b32_e32 v64, v125
	v_mov_b32_e32 v63, v125
	v_mov_b32_e32 v62, v125
	v_mov_b32_e32 v41, v125
	v_mov_b32_e32 v40, v125
	v_mov_b32_e32 v39, v125
	v_mov_b32_e32 v38, v125
	v_mov_b32_e32 v61, v125
	v_mov_b32_e32 v60, v125
	v_mov_b32_e32 v59, v125
	v_mov_b32_e32 v58, v125
	s_cbranch_vccnz .LBB0_741
	s_add_u32 s2, s46, 0x80
	s_addc_u32 s3, s47, 0
	s_add_u32 s46, s44, 0x100
	s_addc_u32 s47, s45, 0
	s_mov_b32 s44, 0
	s_mov_b64 vcc, 0x80

.LBB0_887:
	v_mov_b32_e32 v129, 0
	s_andn2_b64 vcc, exec, s[12:13]
	v_mov_b32_e32 v128, v129
	v_mov_b32_e32 v127, v129
	v_mov_b32_e32 v126, v129
	v_mov_b32_e32 v125, v129
	v_mov_b32_e32 v124, v129
	v_mov_b32_e32 v123, v129
	v_mov_b32_e32 v122, v129
	v_mov_b32_e32 v113, v129
	v_mov_b32_e32 v112, v129
	v_mov_b32_e32 v111, v129
	v_mov_b32_e32 v110, v129
	v_mov_b32_e32 v109, v129
	v_mov_b32_e32 v108, v129
	v_mov_b32_e32 v107, v129
	v_mov_b32_e32 v106, v129
	s_waitcnt vmcnt(0)
	v_mov_b32_e32 v97, v129
	v_mov_b32_e32 v96, v129
	v_mov_b32_e32 v95, v129
	v_mov_b32_e32 v94, v129
	v_mov_b32_e32 v93, v129
	v_mov_b32_e32 v92, v129
	v_mov_b32_e32 v91, v129
	v_mov_b32_e32 v90, v129
	v_mov_b32_e32 v81, v129
	v_mov_b32_e32 v80, v129
	v_mov_b32_e32 v79, v129
	v_mov_b32_e32 v78, v129
	v_mov_b32_e32 v77, v129
	v_mov_b32_e32 v76, v129
	v_mov_b32_e32 v75, v129
	v_mov_b32_e32 v74, v129
	v_mov_b32_e32 v121, v129
	v_mov_b32_e32 v120, v129
	v_mov_b32_e32 v119, v129
	v_mov_b32_e32 v118, v129
	v_mov_b32_e32 v117, v129
	v_mov_b32_e32 v116, v129
	v_mov_b32_e32 v115, v129
	v_mov_b32_e32 v114, v129
	v_mov_b32_e32 v105, v129
	v_mov_b32_e32 v104, v129
	v_mov_b32_e32 v103, v129
	v_mov_b32_e32 v102, v129
	v_mov_b32_e32 v101, v129
	v_mov_b32_e32 v100, v129
	v_mov_b32_e32 v99, v129
	v_mov_b32_e32 v98, v129
	v_mov_b32_e32 v89, v129
	v_mov_b32_e32 v88, v129
	v_mov_b32_e32 v87, v129
	v_mov_b32_e32 v86, v129
	v_mov_b32_e32 v85, v129
	v_mov_b32_e32 v84, v129
	v_mov_b32_e32 v83, v129
	v_mov_b32_e32 v82, v129
	v_mov_b32_e32 v73, v129
	v_mov_b32_e32 v72, v129
	v_mov_b32_e32 v71, v129
	v_mov_b32_e32 v70, v129
	v_mov_b32_e32 v69, v129
	v_mov_b32_e32 v68, v129
	v_mov_b32_e32 v67, v129
	v_mov_b32_e32 v66, v129
	v_mov_b32_e32 v65, v129
	v_mov_b32_e32 v64, v129
	v_mov_b32_e32 v63, v129
	v_mov_b32_e32 v62, v129
	v_mov_b32_e32 v61, v129
	v_mov_b32_e32 v60, v129
	v_mov_b32_e32 v59, v129
	v_mov_b32_e32 v58, v129
	v_mov_b32_e32 v49, v129
	v_mov_b32_e32 v48, v129
	v_mov_b32_e32 v47, v129
	v_mov_b32_e32 v46, v129
	v_mov_b32_e32 v45, v129
	v_mov_b32_e32 v44, v129
	v_mov_b32_e32 v43, v129
	v_mov_b32_e32 v42, v129
	v_mov_b32_e32 v33, v129
	v_mov_b32_e32 v32, v129
	v_mov_b32_e32 v31, v129
	v_mov_b32_e32 v30, v129
	v_mov_b32_e32 v29, v129
	v_mov_b32_e32 v28, v129
	v_mov_b32_e32 v27, v129
	v_mov_b32_e32 v26, v129
	v_mov_b32_e32 v17, v129
	v_mov_b32_e32 v16, v129
	v_mov_b32_e32 v15, v129
	v_mov_b32_e32 v14, v129
	v_mov_b32_e32 v13, v129
	v_mov_b32_e32 v12, v129
	v_mov_b32_e32 v11, v129
	v_mov_b32_e32 v10, v129
	v_mov_b32_e32 v57, v129
	v_mov_b32_e32 v56, v129
	v_mov_b32_e32 v55, v129
	v_mov_b32_e32 v54, v129
	v_mov_b32_e32 v53, v129
	v_mov_b32_e32 v52, v129
	v_mov_b32_e32 v51, v129
	v_mov_b32_e32 v50, v129
	v_mov_b32_e32 v41, v129
	v_mov_b32_e32 v40, v129
	v_mov_b32_e32 v39, v129
	v_mov_b32_e32 v38, v129
	v_mov_b32_e32 v37, v129
	v_mov_b32_e32 v36, v129
	v_mov_b32_e32 v35, v129
	v_mov_b32_e32 v34, v129
	v_mov_b32_e32 v25, v129
	v_mov_b32_e32 v24, v129
	v_mov_b32_e32 v23, v129
	v_mov_b32_e32 v22, v129
	v_mov_b32_e32 v21, v129
	v_mov_b32_e32 v20, v129
	v_mov_b32_e32 v19, v129
	v_mov_b32_e32 v18, v129
	v_mov_b32_e32 v9, v129
	v_mov_b32_e32 v8, v129
	v_mov_b32_e32 v7, v129
	v_mov_b32_e32 v6, v129
	v_mov_b32_e32 v5, v129
	v_mov_b32_e32 v4, v129
	v_mov_b32_e32 v3, v129
	v_mov_b32_e32 v2, v129
	s_cbranch_vccnz .LBB0_890
	s_add_u32 s18, s18, 0x80
	s_addc_u32 s19, s19, 0
	s_add_u32 s43, s20, 0x100
	s_addc_u32 s44, s21, 0
	s_mov_b32 s20, 0
	s_mov_b64 s[50:51], 0x80
